# v19 = v18 + ktime<2> software prefetch of the next filter-tap tile's 6 global loads during the exp/store phase (into free VGPRs, copied at loop top)
# speedup vs baseline: 1.0071x; 1.0008x over previous
.LBB0_615:
	s_or_b64 exec, exec, s[48:49]
	s_mov_b64 s[2:3], s[96:97]
	s_mov_b32 s5, s93
	s_mov_b32 s4, s94
	s_add_i32 s6, s5, 0x400
	s_cmpk_eq_i32 s4, 0x100
	s_cselect_b32 s5, s6, s5
	v_mov_b32_e32 v0, v192
	s_cmpk_lt_i32 s5, 0x800
	s_movk_i32 s8, 0x800
	s_cbranch_scc0 .LBB0_625
	s_load_dwordx2 s[6:7], s[2:3], 0x50
	s_load_dwordx4 s[40:43], s[2:3], 0xc0
	v_readlane_b32 s8, v255, 20
	v_readlane_b32 s9, v255, 21
	s_mov_b32 s9, s75
	s_lshl_b64 s[2:3], s[8:9], 21
	s_mov_b32 s10, s8
	s_lshl_b64 s[8:9], s[8:9], 19
	s_waitcnt lgkmcnt(0)
	s_add_u32 s6, s6, s8
	s_addc_u32 s7, s7, s9
	v_lshlrev_b32_e32 v1, 2, v0
	s_add_u32 s2, s42, s2
	v_and_b32_e32 v4, 60, v1
	s_addc_u32 s3, s43, s3
	v_lshlrev_b32_e32 v194, 2, v4
	v_lshl_add_u64 v[2:3], s[2:3], 0, v[194:195]
	s_mov_b64 s[2:3], 0x22200000
	v_and_b32_e32 v21, 0x7c, v1
	v_lshlrev_b32_e32 v1, 4, v0
	v_lshl_add_u64 v[16:17], v[2:3], 0, s[2:3]
	s_movk_i32 s2, 0x210
	v_ashrrev_i32_e32 v34, 3, v0
	v_and_b32_e32 v20, 0x70, v1
	v_mad_u32_u24 v2, v4, s2, 0
	v_mul_i32_i24_e32 v3, 0xfffffdf4, v4
	v_mul_lo_u32 v4, v34, s2
	v_lshlrev_b32_e32 v5, 2, v20
	v_add3_u32 v37, 0, v4, v5
	v_add_u32_e32 v4, 0x200, v0
	v_ashrrev_i32_e32 v22, 4, v0
	v_ashrrev_i32_e32 v24, 4, v4
	v_add_u32_e32 v4, 0x400, v0
	v_add_u32_e32 v0, 0x600, v0
	v_writelane_b32 v255, s10, 20
	v_ashrrev_i32_e32 v38, 4, v4
	v_ashrrev_i32_e32 v39, 4, v0
	v_ashrrev_i32_e32 v23, 31, v22
	v_ashrrev_i32_e32 v25, 31, v24
	v_and_b32_e32 v0, 0xffffff00, v1
	v_writelane_b32 v255, s11, 21
	v_and_b32_e32 v35, -4, v34
	v_lshlrev_b64 v[26:27], 13, v[22:23]
	v_lshlrev_b64 v[28:29], 13, v[24:25]
	v_lshl_add_u32 v23, v22, 2, v2
	v_lshl_add_u32 v25, v24, 2, v2
	v_lshl_add_u32 v40, v38, 2, v2
	v_lshl_add_u32 v41, v39, 2, v2
	v_add3_u32 v42, v2, v3, v0
	v_or_b32_e32 v1, 3, v34
	v_lshlrev_b32_e32 v2, 2, v34
	v_lshl_add_u32 v36, v21, 2, 0
	v_mul_lo_u32 v0, v35, s2
	v_mul_lo_u32 v1, v1, s2
	v_and_b32_e32 v2, -16, v2
	v_readlane_b32 s2, v255, 8
	v_lshl_add_u64 v[18:19], s[6:7], 0, v[194:195]
	v_add_u32_e32 v44, v36, v0
	v_add_u32_e32 v43, s2, v2
	v_add_u32_e32 v45, v36, v1
	s_mov_b32 s90, s5
	s_lshl_b32 s91, s90, 2
	s_and_b32 s91, s91, 0xffffff80
	s_lshl_b32 s92, s90, 6
	s_and_b32 s92, s92, 0x7c0
	s_lshl_b32 s98, s92, 2
	s_mov_b32 s99, 0
	v_add_u32_e32 v136, s91, v22
	v_ashrrev_i32_e32 v137, 31, v136
	v_lshlrev_b64 v[136:137], 8, v[136:137]
	v_lshl_add_u64 v[138:139], v[16:17], 0, v[136:137]
	v_add_u32_e32 v136, s91, v24
	v_ashrrev_i32_e32 v137, 31, v136
	v_lshlrev_b64 v[136:137], 8, v[136:137]
	v_lshl_add_u64 v[140:141], v[16:17], 0, v[136:137]
	v_add_u32_e32 v136, s91, v38
	v_ashrrev_i32_e32 v137, 31, v136
	v_lshlrev_b64 v[136:137], 8, v[136:137]
	v_lshl_add_u64 v[142:143], v[16:17], 0, v[136:137]
	v_add_u32_e32 v136, s91, v39
	v_ashrrev_i32_e32 v137, 31, v136
	v_lshlrev_b64 v[136:137], 8, v[136:137]
	v_lshl_add_u64 v[144:145], v[16:17], 0, v[136:137]
	v_lshl_add_u64 v[146:147], v[18:19], 0, s[98:99]
	v_lshl_add_u64 v[148:149], v[146:147], 0, v[26:27]
	v_lshl_add_u64 v[150:151], v[146:147], 0, v[28:29]
	global_load_dwordx4 v[112:115], v[144:145], off
	global_load_dwordx4 v[116:119], v[142:143], off
	global_load_dwordx4 v[120:123], v[140:141], off
	global_load_dwordx4 v[124:127], v[138:139], off
	global_load_dwordx4 v[128:131], v[150:151], off
	global_load_dwordx4 v[132:135], v[148:149], off
	s_branch .LBB0_618

.LBB0_618:
	s_lshl_b32 s2, s5, 2
	s_and_b32 s42, s2, 0xffffff80
	s_lshl_b32 s2, s5, 6
	s_and_b32 s3, s2, 0x7c0
	s_barrier
	s_mov_b32 s6, 0
	s_waitcnt vmcnt(0)
	v_mov_b64_e32 v[0:1], v[112:113]
	v_mov_b64_e32 v[2:3], v[114:115]
	v_mov_b64_e32 v[4:5], v[116:117]
	v_mov_b64_e32 v[6:7], v[118:119]
	v_mov_b64_e32 v[8:9], v[120:121]
	v_mov_b64_e32 v[10:11], v[122:123]
	v_mov_b64_e32 v[12:13], v[124:125]
	v_mov_b64_e32 v[14:15], v[126:127]
	v_mov_b64_e32 v[30:31], v[128:129]
	v_mov_b64_e32 v[32:33], v[130:131]
	v_mov_b64_e32 v[46:47], v[132:133]
	v_mov_b64_e32 v[48:49], v[134:135]
	ds_write2_b32 v23, v12, v13 offset1:132
	v_add_u32_e32 v12, 0x400, v23
	ds_write2_b32 v12, v14, v15 offset0:8 offset1:140
	ds_write2_b32 v25, v8, v9 offset1:132
	v_add_u32_e32 v8, 0x400, v25
	ds_write2_b32 v8, v10, v11 offset0:8 offset1:140
	ds_write2_b32 v40, v4, v5 offset1:132
	v_add_u32_e32 v4, 0x400, v40
	ds_write2_b32 v4, v6, v7 offset0:8 offset1:140
	ds_write2_b32 v41, v0, v1 offset1:132
	v_add_u32_e32 v0, 0x400, v41
	ds_write2_b32 v0, v2, v3 offset0:8 offset1:140
	ds_write_b128 v42, v[46:49] offset:33792
	ds_write_b128 v42, v[30:33] offset:41984
	v_mov_b32_e32 v0, 0
	v_mov_b32_e32 v30, v36
	v_mov_b32_e32 v1, v0
	v_mov_b32_e32 v2, v0
	v_mov_b32_e32 v3, v0
	v_mov_b32_e32 v12, v0
	v_mov_b32_e32 v13, v0
	v_mov_b32_e32 v14, v0
	v_mov_b32_e32 v15, v0
	v_mov_b32_e32 v8, v0
	v_mov_b32_e32 v9, v0
	v_mov_b32_e32 v10, v0
	v_mov_b32_e32 v11, v0
	v_mov_b32_e32 v4, v0
	v_mov_b32_e32 v5, v0
	v_mov_b32_e32 v6, v0
	v_mov_b32_e32 v7, v0
	s_waitcnt lgkmcnt(0)
	s_barrier
.LBB0_619:
	v_add_u32_e32 v31, s6, v43
	ds_read_b128 v[46:49], v30
	ds_read_b128 v[50:53], v31
	s_addk_i32 s6, 0x800
	s_cmpk_eq_i32 s6, 0x4000
	s_waitcnt lgkmcnt(0)
	v_pk_fma_f32 v[14:15], v[48:49], v[50:51], v[14:15] op_sel_hi:[1,0,1]
	v_pk_fma_f32 v[12:13], v[46:47], v[50:51], v[12:13] op_sel_hi:[1,0,1]
	v_pk_fma_f32 v[10:11], v[48:49], v[50:51], v[10:11] op_sel:[0,1,0]
	v_pk_fma_f32 v[8:9], v[46:47], v[50:51], v[8:9] op_sel:[0,1,0]
	v_pk_fma_f32 v[50:51], v[46:47], v[52:53], v[4:5] op_sel_hi:[1,0,1]
	v_mov_b32_e32 v4, v53
	v_pk_fma_f32 v[32:33], v[48:49], v[52:53], v[6:7] op_sel_hi:[1,0,1]
	v_pk_fma_f32 v[48:49], v[48:49], v[4:5], v[2:3] op_sel_hi:[1,0,1]
	v_pk_fma_f32 v[46:47], v[46:47], v[4:5], v[0:1] op_sel_hi:[1,0,1]
	ds_read_b128 v[0:3], v30 offset:528
	ds_read_b128 v[4:7], v31 offset:256
	s_waitcnt lgkmcnt(0)
	v_pk_fma_f32 v[14:15], v[2:3], v[4:5], v[14:15] op_sel_hi:[1,0,1]
	v_pk_fma_f32 v[12:13], v[0:1], v[4:5], v[12:13] op_sel_hi:[1,0,1]
	v_pk_fma_f32 v[10:11], v[2:3], v[4:5], v[10:11] op_sel:[0,1,0]
	v_pk_fma_f32 v[8:9], v[0:1], v[4:5], v[8:9] op_sel:[0,1,0]
	v_mov_b32_e32 v4, v7
	v_pk_fma_f32 v[32:33], v[2:3], v[6:7], v[32:33] op_sel_hi:[1,0,1]
	v_pk_fma_f32 v[50:51], v[0:1], v[6:7], v[50:51] op_sel_hi:[1,0,1]
	v_pk_fma_f32 v[48:49], v[2:3], v[4:5], v[48:49] op_sel_hi:[1,0,1]
	v_pk_fma_f32 v[46:47], v[0:1], v[4:5], v[46:47] op_sel_hi:[1,0,1]
	ds_read_b128 v[0:3], v30 offset:1056
	ds_read_b128 v[4:7], v31 offset:512
	s_waitcnt lgkmcnt(0)
	v_pk_fma_f32 v[14:15], v[2:3], v[4:5], v[14:15] op_sel_hi:[1,0,1]
	v_pk_fma_f32 v[12:13], v[0:1], v[4:5], v[12:13] op_sel_hi:[1,0,1]
	v_pk_fma_f32 v[10:11], v[2:3], v[4:5], v[10:11] op_sel:[0,1,0]
	v_pk_fma_f32 v[8:9], v[0:1], v[4:5], v[8:9] op_sel:[0,1,0]
	v_mov_b32_e32 v4, v7
	v_pk_fma_f32 v[32:33], v[2:3], v[6:7], v[32:33] op_sel_hi:[1,0,1]
	v_pk_fma_f32 v[50:51], v[0:1], v[6:7], v[50:51] op_sel_hi:[1,0,1]
	v_pk_fma_f32 v[48:49], v[2:3], v[4:5], v[48:49] op_sel_hi:[1,0,1]
	v_pk_fma_f32 v[46:47], v[0:1], v[4:5], v[46:47] op_sel_hi:[1,0,1]
	ds_read_b128 v[0:3], v30 offset:1584
	ds_read_b128 v[4:7], v31 offset:768
	s_waitcnt lgkmcnt(0)
	v_pk_fma_f32 v[14:15], v[2:3], v[4:5], v[14:15] op_sel_hi:[1,0,1]
	v_pk_fma_f32 v[12:13], v[0:1], v[4:5], v[12:13] op_sel_hi:[1,0,1]
	v_pk_fma_f32 v[10:11], v[2:3], v[4:5], v[10:11] op_sel:[0,1,0]
	v_pk_fma_f32 v[8:9], v[0:1], v[4:5], v[8:9] op_sel:[0,1,0]
	v_mov_b32_e32 v4, v7
	v_pk_fma_f32 v[32:33], v[2:3], v[6:7], v[32:33] op_sel_hi:[1,0,1]
	v_pk_fma_f32 v[50:51], v[0:1], v[6:7], v[50:51] op_sel_hi:[1,0,1]
	v_pk_fma_f32 v[48:49], v[2:3], v[4:5], v[48:49] op_sel_hi:[1,0,1]
	v_pk_fma_f32 v[46:47], v[0:1], v[4:5], v[46:47] op_sel_hi:[1,0,1]
	ds_read_b128 v[0:3], v30 offset:2112
	ds_read_b128 v[4:7], v31 offset:1024
	s_waitcnt lgkmcnt(0)
	v_pk_fma_f32 v[14:15], v[2:3], v[4:5], v[14:15] op_sel_hi:[1,0,1]
	v_pk_fma_f32 v[12:13], v[0:1], v[4:5], v[12:13] op_sel_hi:[1,0,1]
	v_pk_fma_f32 v[10:11], v[2:3], v[4:5], v[10:11] op_sel:[0,1,0]
	v_pk_fma_f32 v[8:9], v[0:1], v[4:5], v[8:9] op_sel:[0,1,0]
	v_mov_b32_e32 v4, v7
	v_pk_fma_f32 v[32:33], v[2:3], v[6:7], v[32:33] op_sel_hi:[1,0,1]
	v_pk_fma_f32 v[50:51], v[0:1], v[6:7], v[50:51] op_sel_hi:[1,0,1]
	v_pk_fma_f32 v[48:49], v[2:3], v[4:5], v[48:49] op_sel_hi:[1,0,1]
	v_pk_fma_f32 v[46:47], v[0:1], v[4:5], v[46:47] op_sel_hi:[1,0,1]
	ds_read_b128 v[0:3], v30 offset:2640
	ds_read_b128 v[4:7], v31 offset:1280
	s_waitcnt lgkmcnt(0)
	v_pk_fma_f32 v[14:15], v[2:3], v[4:5], v[14:15] op_sel_hi:[1,0,1]
	v_pk_fma_f32 v[12:13], v[0:1], v[4:5], v[12:13] op_sel_hi:[1,0,1]
	v_pk_fma_f32 v[10:11], v[2:3], v[4:5], v[10:11] op_sel:[0,1,0]
	v_pk_fma_f32 v[8:9], v[0:1], v[4:5], v[8:9] op_sel:[0,1,0]
	v_mov_b32_e32 v4, v7
	v_pk_fma_f32 v[32:33], v[2:3], v[6:7], v[32:33] op_sel_hi:[1,0,1]
	v_pk_fma_f32 v[50:51], v[0:1], v[6:7], v[50:51] op_sel_hi:[1,0,1]
	v_pk_fma_f32 v[48:49], v[2:3], v[4:5], v[48:49] op_sel_hi:[1,0,1]
	v_pk_fma_f32 v[46:47], v[0:1], v[4:5], v[46:47] op_sel_hi:[1,0,1]
	ds_read_b128 v[0:3], v30 offset:3168
	ds_read_b128 v[4:7], v31 offset:1536
	s_waitcnt lgkmcnt(0)
	v_pk_fma_f32 v[32:33], v[2:3], v[6:7], v[32:33] op_sel_hi:[1,0,1]
	v_pk_fma_f32 v[50:51], v[0:1], v[6:7], v[50:51] op_sel_hi:[1,0,1]
	v_mov_b32_e32 v6, v7
	v_pk_fma_f32 v[14:15], v[2:3], v[4:5], v[14:15] op_sel_hi:[1,0,1]
	v_pk_fma_f32 v[12:13], v[0:1], v[4:5], v[12:13] op_sel_hi:[1,0,1]
	v_pk_fma_f32 v[10:11], v[2:3], v[4:5], v[10:11] op_sel:[0,1,0]
	v_pk_fma_f32 v[4:5], v[0:1], v[4:5], v[8:9] op_sel:[0,1,0]
	v_pk_fma_f32 v[52:53], v[2:3], v[6:7], v[48:49] op_sel_hi:[1,0,1]
	v_pk_fma_f32 v[54:55], v[0:1], v[6:7], v[46:47] op_sel_hi:[1,0,1]
	ds_read_b128 v[0:3], v30 offset:3696
	ds_read_b128 v[46:49], v31 offset:1792
	v_add_u32_e32 v30, 0x1080, v30
	s_waitcnt lgkmcnt(0)
	v_pk_fma_f32 v[6:7], v[2:3], v[48:49], v[32:33] op_sel_hi:[1,0,1]
	v_mov_b32_e32 v32, v49
	v_pk_fma_f32 v[14:15], v[2:3], v[46:47], v[14:15] op_sel_hi:[1,0,1]
	v_pk_fma_f32 v[12:13], v[0:1], v[46:47], v[12:13] op_sel_hi:[1,0,1]
	v_pk_fma_f32 v[10:11], v[2:3], v[46:47], v[10:11] op_sel:[0,1,0]
	v_pk_fma_f32 v[8:9], v[0:1], v[46:47], v[4:5] op_sel:[0,1,0]
	v_pk_fma_f32 v[4:5], v[0:1], v[48:49], v[50:51] op_sel_hi:[1,0,1]
	v_pk_fma_f32 v[2:3], v[2:3], v[32:33], v[52:53] op_sel_hi:[1,0,1]
	v_pk_fma_f32 v[0:1], v[0:1], v[32:33], v[54:55] op_sel_hi:[1,0,1]
	s_cbranch_scc0 .LBB0_619
	s_add_i32 s90, s5, s4
	s_cmpk_lt_i32 s90, 0x800
	s_cbranch_scc0 .Lkt2_pf_skip
	s_lshl_b32 s91, s90, 2
	s_and_b32 s91, s91, 0xffffff80
	s_lshl_b32 s92, s90, 6
	s_and_b32 s92, s92, 0x7c0
	s_lshl_b32 s98, s92, 2
	s_mov_b32 s99, 0
	v_add_u32_e32 v136, s91, v22
	v_ashrrev_i32_e32 v137, 31, v136
	v_lshlrev_b64 v[136:137], 8, v[136:137]
	v_lshl_add_u64 v[138:139], v[16:17], 0, v[136:137]
	v_add_u32_e32 v136, s91, v24
	v_ashrrev_i32_e32 v137, 31, v136
	v_lshlrev_b64 v[136:137], 8, v[136:137]
	v_lshl_add_u64 v[140:141], v[16:17], 0, v[136:137]
	v_add_u32_e32 v136, s91, v38
	v_ashrrev_i32_e32 v137, 31, v136
	v_lshlrev_b64 v[136:137], 8, v[136:137]
	v_lshl_add_u64 v[142:143], v[16:17], 0, v[136:137]
	v_add_u32_e32 v136, s91, v39
	v_ashrrev_i32_e32 v137, 31, v136
	v_lshlrev_b64 v[136:137], 8, v[136:137]
	v_lshl_add_u64 v[144:145], v[16:17], 0, v[136:137]
	v_lshl_add_u64 v[146:147], v[18:19], 0, s[98:99]
	v_lshl_add_u64 v[148:149], v[146:147], 0, v[26:27]
	v_lshl_add_u64 v[150:151], v[146:147], 0, v[28:29]
	global_load_dwordx4 v[112:115], v[144:145], off
	global_load_dwordx4 v[116:119], v[142:143], off
	global_load_dwordx4 v[120:123], v[140:141], off
	global_load_dwordx4 v[124:127], v[138:139], off
	global_load_dwordx4 v[128:131], v[150:151], off
	global_load_dwordx4 v[132:135], v[148:149], off
.Lkt2_pf_skip:
	v_or_b32_e32 v46, s42, v21
	v_cvt_f32_i32_e32 v31, v46
	v_add_u32_e32 v30, s2, v35
	v_and_b32_e32 v30, 0x3fc, v30
	v_div_scale_f32 v32, s[6:7], s33, s33, v31
	v_rcp_f32_e32 v33, v32
	s_barrier
	s_cmpk_lt_u32 s3, 0x400
	v_fma_f32 v47, -v32, v33, 1.0
	v_fmac_f32_e32 v33, v47, v33
	v_div_scale_f32 v47, vcc, v31, s33, v31
	v_mul_f32_e32 v48, v47, v33
	v_fma_f32 v49, -v32, v48, v47
	v_fmac_f32_e32 v48, v49, v33
	v_fma_f32 v32, -v32, v48, v47
	v_div_fmas_f32 v32, v32, v33, v48
	v_div_fixup_f32 v31, v32, s33, v31
	v_cvt_f32_u32_e32 v32, v30
	v_fmamk_f32 v47, v32, 0x3c44ade8, v193
	v_mul_f32_e64 v32, v31, |v47|
	v_mul_f32_e32 v33, 0x3fb8aa3b, v32
	v_fma_f32 v48, v32, s78, -v33
	v_rndne_f32_e32 v49, v33
	v_fmac_f32_e32 v48, 0x32a5705f, v32
	v_sub_f32_e32 v33, v33, v49
	v_add_f32_e32 v33, v33, v48
	v_exp_f32_e32 v33, v33
	v_cvt_i32_f32_e32 v48, v49
	v_cmp_ngt_f32_e32 vcc, s79, v32
	v_ldexp_f32 v33, v33, v48
	s_nop 0
	v_cndmask_b32_e32 v33, 0, v33, vcc
	v_cmp_nlt_f32_e32 vcc, s80, v32
	v_or_b32_e32 v32, 1, v46
	v_cvt_f32_i32_e32 v32, v32
	v_cndmask_b32_e32 v48, v244, v33, vcc
	v_div_scale_f32 v33, s[6:7], s33, s33, v32
	v_rcp_f32_e32 v49, v33
	s_nop 0
	v_fma_f32 v50, -v33, v49, 1.0
	v_fmac_f32_e32 v49, v50, v49
	v_div_scale_f32 v50, vcc, v32, s33, v32
	v_mul_f32_e32 v51, v50, v49
	v_fma_f32 v52, -v33, v51, v50
	v_fmac_f32_e32 v51, v52, v49
	v_fma_f32 v33, -v33, v51, v50
	v_div_fmas_f32 v33, v33, v49, v51
	v_div_fixup_f32 v32, v33, s33, v32
	v_mul_f32_e64 v33, v32, |v47|
	v_mul_f32_e32 v49, 0x3fb8aa3b, v33
	v_fma_f32 v50, v33, s78, -v49
	v_rndne_f32_e32 v51, v49
	v_fmac_f32_e32 v50, 0x32a5705f, v33
	v_sub_f32_e32 v49, v49, v51
	v_add_f32_e32 v49, v49, v50
	v_exp_f32_e32 v49, v49
	v_cvt_i32_f32_e32 v50, v51
	v_cmp_ngt_f32_e32 vcc, s79, v33
	v_ldexp_f32 v49, v49, v50
	s_nop 0
	v_cndmask_b32_e32 v49, 0, v49, vcc
	v_cmp_nlt_f32_e32 vcc, s80, v33
	v_or_b32_e32 v33, 2, v46
	v_cvt_f32_i32_e32 v33, v33
	v_cndmask_b32_e32 v49, v244, v49, vcc
	v_or_b32_e32 v46, 3, v46
	v_cvt_f32_i32_e32 v46, v46
	v_div_scale_f32 v50, s[6:7], s33, s33, v33
	v_rcp_f32_e32 v51, v50
	v_pk_mul_f32 v[12:13], v[48:49], v[12:13]
	v_fma_f32 v52, -v50, v51, 1.0
	v_fmac_f32_e32 v51, v52, v51
	v_div_scale_f32 v52, vcc, v33, s33, v33
	v_mul_f32_e32 v53, v52, v51
	v_fma_f32 v54, -v50, v53, v52
	v_fmac_f32_e32 v53, v54, v51
	v_fma_f32 v50, -v50, v53, v52
	v_div_fmas_f32 v50, v50, v51, v53
	v_div_fixup_f32 v33, v50, s33, v33
	v_mul_f32_e64 v50, v33, |v47|
	v_mul_f32_e32 v51, 0x3fb8aa3b, v50
	v_fma_f32 v52, v50, s78, -v51
	v_rndne_f32_e32 v53, v51
	v_fmac_f32_e32 v52, 0x32a5705f, v50
	v_sub_f32_e32 v51, v51, v53
	v_add_f32_e32 v51, v51, v52
	v_exp_f32_e32 v51, v51
	v_cvt_i32_f32_e32 v52, v53
	v_cmp_ngt_f32_e32 vcc, s79, v50
	v_ldexp_f32 v51, v51, v52
	s_nop 0
	v_cndmask_b32_e32 v51, 0, v51, vcc
	v_cmp_nlt_f32_e32 vcc, s80, v50
	s_nop 1
	v_cndmask_b32_e32 v50, v244, v51, vcc
	v_div_scale_f32 v51, s[6:7], s33, s33, v46
	v_rcp_f32_e32 v52, v51
	s_nop 0
	v_fma_f32 v53, -v51, v52, 1.0
	v_fmac_f32_e32 v52, v53, v52
	v_div_scale_f32 v53, vcc, v46, s33, v46
	v_mul_f32_e32 v54, v53, v52
	v_fma_f32 v55, -v51, v54, v53
	v_fmac_f32_e32 v54, v55, v52
	v_fma_f32 v51, -v51, v54, v53
	v_div_fmas_f32 v51, v51, v52, v54
	v_div_fixup_f32 v46, v51, s33, v46
	v_mul_f32_e64 v47, v46, |v47|
	v_mul_f32_e32 v51, 0x3fb8aa3b, v47
	v_fma_f32 v52, v47, s78, -v51
	v_rndne_f32_e32 v53, v51
	v_fmac_f32_e32 v52, 0x32a5705f, v47
	v_sub_f32_e32 v51, v51, v53
	v_add_f32_e32 v51, v51, v52
	v_exp_f32_e32 v51, v51
	v_cvt_i32_f32_e32 v52, v53
	v_cmp_ngt_f32_e32 vcc, s79, v47
	v_ldexp_f32 v51, v51, v52
	s_nop 0
	v_cndmask_b32_e32 v51, 0, v51, vcc
	v_cmp_nlt_f32_e32 vcc, s80, v47
	s_nop 1
	v_cndmask_b32_e32 v51, v244, v51, vcc
	v_pk_mul_f32 v[14:15], v[50:51], v[14:15]
	ds_write_b128 v44, v[12:15]
	v_or_b32_e32 v12, 1, v30
	v_cvt_f32_u32_e32 v12, v12
	v_fmamk_f32 v15, v12, 0x3c44ade8, v193
	v_mul_f32_e64 v12, v31, |v15|
	v_mul_f32_e32 v13, 0x3fb8aa3b, v12
	v_fma_f32 v14, v12, s78, -v13
	v_rndne_f32_e32 v47, v13
	v_fmac_f32_e32 v14, 0x32a5705f, v12
	v_sub_f32_e32 v13, v13, v47
	v_add_f32_e32 v13, v13, v14
	v_exp_f32_e32 v13, v13
	v_cvt_i32_f32_e32 v14, v47
	v_cmp_ngt_f32_e32 vcc, s79, v12
	v_ldexp_f32 v13, v13, v14
	s_nop 0
	v_cndmask_b32_e32 v13, 0, v13, vcc
	v_cmp_nlt_f32_e32 vcc, s80, v12
	s_nop 1
	v_cndmask_b32_e32 v12, v244, v13, vcc
	v_mul_f32_e64 v13, v32, |v15|
	v_mul_f32_e32 v14, 0x3fb8aa3b, v13
	v_fma_f32 v47, v13, s78, -v14
	v_rndne_f32_e32 v48, v14
	v_fmac_f32_e32 v47, 0x32a5705f, v13
	v_sub_f32_e32 v14, v14, v48
	v_add_f32_e32 v14, v14, v47
	v_exp_f32_e32 v14, v14
	v_cvt_i32_f32_e32 v47, v48
	v_cmp_ngt_f32_e32 vcc, s79, v13
	v_ldexp_f32 v14, v14, v47
	s_nop 0
	v_cndmask_b32_e32 v14, 0, v14, vcc
	v_cmp_nlt_f32_e32 vcc, s80, v13
	s_nop 1
	v_cndmask_b32_e32 v13, v244, v14, vcc
	v_mul_f32_e64 v14, v33, |v15|
	v_mul_f32_e32 v47, 0x3fb8aa3b, v14
	v_fma_f32 v48, v14, s78, -v47
	v_rndne_f32_e32 v49, v47
	v_fmac_f32_e32 v48, 0x32a5705f, v14
	v_sub_f32_e32 v47, v47, v49
	v_add_f32_e32 v47, v47, v48
	v_exp_f32_e32 v47, v47
	v_cvt_i32_f32_e32 v48, v49
	v_cmp_ngt_f32_e32 vcc, s79, v14
	v_mul_f32_e64 v15, v46, |v15|
	v_pk_mul_f32 v[8:9], v[12:13], v[8:9]
	v_ldexp_f32 v47, v47, v48
	v_cndmask_b32_e32 v47, 0, v47, vcc
	v_cmp_nlt_f32_e32 vcc, s80, v14
	s_nop 1
	v_cndmask_b32_e32 v14, v244, v47, vcc
	v_mul_f32_e32 v47, 0x3fb8aa3b, v15
	v_fma_f32 v48, v15, s78, -v47
	v_rndne_f32_e32 v49, v47
	v_fmac_f32_e32 v48, 0x32a5705f, v15
	v_sub_f32_e32 v47, v47, v49
	v_add_f32_e32 v47, v47, v48
	v_exp_f32_e32 v47, v47
	v_cvt_i32_f32_e32 v48, v49
	v_cmp_ngt_f32_e32 vcc, s79, v15
	v_ldexp_f32 v47, v47, v48
	s_nop 0
	v_cndmask_b32_e32 v47, 0, v47, vcc
	v_cmp_nlt_f32_e32 vcc, s80, v15
	s_nop 1
	v_cndmask_b32_e32 v15, v244, v47, vcc
	v_pk_mul_f32 v[10:11], v[14:15], v[10:11]
	ds_write_b128 v44, v[8:11] offset:528
	v_or_b32_e32 v8, 2, v30
	v_cvt_f32_u32_e32 v8, v8
	v_fmamk_f32 v11, v8, 0x3c44ade8, v193
	v_mul_f32_e64 v8, v31, |v11|
	v_mul_f32_e32 v9, 0x3fb8aa3b, v8
	v_fma_f32 v10, v8, s78, -v9
	v_rndne_f32_e32 v12, v9
	v_fmac_f32_e32 v10, 0x32a5705f, v8
	v_sub_f32_e32 v9, v9, v12
	v_add_f32_e32 v9, v9, v10
	v_exp_f32_e32 v9, v9
	v_cvt_i32_f32_e32 v10, v12
	v_cmp_ngt_f32_e32 vcc, s79, v8
	v_ldexp_f32 v9, v9, v10
	s_nop 0
	v_cndmask_b32_e32 v9, 0, v9, vcc
	v_cmp_nlt_f32_e32 vcc, s80, v8
	s_nop 1
	v_cndmask_b32_e32 v8, v244, v9, vcc
	v_mul_f32_e64 v9, v32, |v11|
	v_mul_f32_e32 v10, 0x3fb8aa3b, v9
	v_fma_f32 v12, v9, s78, -v10
	v_rndne_f32_e32 v13, v10
	v_fmac_f32_e32 v12, 0x32a5705f, v9
	v_sub_f32_e32 v10, v10, v13
	v_add_f32_e32 v10, v10, v12
	v_exp_f32_e32 v10, v10
	v_cvt_i32_f32_e32 v12, v13
	v_cmp_ngt_f32_e32 vcc, s79, v9
	v_ldexp_f32 v10, v10, v12
	s_nop 0
	v_cndmask_b32_e32 v10, 0, v10, vcc
	v_cmp_nlt_f32_e32 vcc, s80, v9
	s_nop 1
	v_cndmask_b32_e32 v9, v244, v10, vcc
	v_mul_f32_e64 v10, v33, |v11|
	v_mul_f32_e32 v12, 0x3fb8aa3b, v10
	v_fma_f32 v13, v10, s78, -v12
	v_rndne_f32_e32 v14, v12
	v_fmac_f32_e32 v13, 0x32a5705f, v10
	v_sub_f32_e32 v12, v12, v14
	v_add_f32_e32 v12, v12, v13
	v_exp_f32_e32 v12, v12
	v_cvt_i32_f32_e32 v13, v14
	v_cmp_ngt_f32_e32 vcc, s79, v10
	v_mul_f32_e64 v11, v46, |v11|
	v_pk_mul_f32 v[4:5], v[8:9], v[4:5]
	v_ldexp_f32 v12, v12, v13
	v_cndmask_b32_e32 v12, 0, v12, vcc
	v_cmp_nlt_f32_e32 vcc, s80, v10
	s_nop 1
	v_cndmask_b32_e32 v10, v244, v12, vcc
	v_mul_f32_e32 v12, 0x3fb8aa3b, v11
	v_fma_f32 v13, v11, s78, -v12
	v_rndne_f32_e32 v14, v12
	v_fmac_f32_e32 v13, 0x32a5705f, v11
	v_sub_f32_e32 v12, v12, v14
	v_add_f32_e32 v12, v12, v13
	v_exp_f32_e32 v12, v12
	v_cvt_i32_f32_e32 v13, v14
	v_cmp_ngt_f32_e32 vcc, s79, v11
	v_ldexp_f32 v12, v12, v13
	s_nop 0
	v_cndmask_b32_e32 v12, 0, v12, vcc
	v_cmp_nlt_f32_e32 vcc, s80, v11
	s_nop 1
	v_cndmask_b32_e32 v11, v244, v12, vcc
	v_pk_mul_f32 v[6:7], v[10:11], v[6:7]
	ds_write_b128 v44, v[4:7] offset:1056
	v_or_b32_e32 v4, 3, v30
	v_cvt_f32_u32_e32 v4, v4
	v_add_lshl_u32 v30, s2, v34, 16
	v_and_b32_e32 v194, 0x3ff0000, v30
	s_mov_b64 s[2:3], -1
	v_fmamk_f32 v7, v4, 0x3c44ade8, v193
	v_mul_f32_e64 v4, v31, |v7|
	v_mul_f32_e32 v5, 0x3fb8aa3b, v4
	v_fma_f32 v6, v4, s78, -v5
	v_rndne_f32_e32 v8, v5
	v_fmac_f32_e32 v6, 0x32a5705f, v4
	v_sub_f32_e32 v5, v5, v8
	v_add_f32_e32 v5, v5, v6
	v_exp_f32_e32 v5, v5
	v_cvt_i32_f32_e32 v6, v8
	v_cmp_ngt_f32_e32 vcc, s79, v4
	v_ldexp_f32 v5, v5, v6
	s_nop 0
	v_cndmask_b32_e32 v5, 0, v5, vcc
	v_cmp_nlt_f32_e32 vcc, s80, v4
	s_nop 1
	v_cndmask_b32_e32 v4, v244, v5, vcc
	v_mul_f32_e64 v5, v32, |v7|
	v_mul_f32_e32 v6, 0x3fb8aa3b, v5
	v_fma_f32 v8, v5, s78, -v6
	v_rndne_f32_e32 v9, v6
	v_fmac_f32_e32 v8, 0x32a5705f, v5
	v_sub_f32_e32 v6, v6, v9
	v_add_f32_e32 v6, v6, v8
	v_exp_f32_e32 v6, v6
	v_cvt_i32_f32_e32 v8, v9
	v_cmp_ngt_f32_e32 vcc, s79, v5
	v_ldexp_f32 v6, v6, v8
	s_nop 0
	v_cndmask_b32_e32 v6, 0, v6, vcc
	v_cmp_nlt_f32_e32 vcc, s80, v5
	s_nop 1
	v_cndmask_b32_e32 v5, v244, v6, vcc
	v_mul_f32_e64 v6, v33, |v7|
	v_mul_f32_e32 v8, 0x3fb8aa3b, v6
	v_fma_f32 v9, v6, s78, -v8
	v_rndne_f32_e32 v10, v8
	v_fmac_f32_e32 v9, 0x32a5705f, v6
	v_sub_f32_e32 v8, v8, v10
	v_add_f32_e32 v8, v8, v9
	v_exp_f32_e32 v8, v8
	v_cvt_i32_f32_e32 v9, v10
	v_cmp_ngt_f32_e32 vcc, s79, v6
	v_mul_f32_e64 v7, v46, |v7|
	v_pk_mul_f32 v[0:1], v[4:5], v[0:1]
	v_ldexp_f32 v8, v8, v9
	v_cndmask_b32_e32 v8, 0, v8, vcc
	v_cmp_nlt_f32_e32 vcc, s80, v6
	v_lshl_add_u64 v[32:33], s[40:41], 0, v[194:195]
	s_nop 0
	v_cndmask_b32_e32 v6, v244, v8, vcc
	v_mul_f32_e32 v8, 0x3fb8aa3b, v7
	v_fma_f32 v9, v7, s78, -v8
	v_rndne_f32_e32 v10, v8
	v_fmac_f32_e32 v9, 0x32a5705f, v7
	v_sub_f32_e32 v8, v8, v10
	v_add_f32_e32 v8, v8, v9
	v_exp_f32_e32 v8, v8
	v_cvt_i32_f32_e32 v9, v10
	v_cmp_ngt_f32_e32 vcc, s79, v7
	v_ldexp_f32 v8, v8, v9
	s_nop 0
	v_cndmask_b32_e32 v8, 0, v8, vcc
	v_cmp_nlt_f32_e32 vcc, s80, v7
	s_nop 1
	v_cndmask_b32_e32 v7, v244, v8, vcc
	v_pk_mul_f32 v[2:3], v[6:7], v[2:3]
	ds_write_b128 v45, v[0:3]
	s_waitcnt lgkmcnt(0)
	s_barrier
	ds_read_b128 v[0:3], v37
	ds_read_b128 v[4:7], v37 offset:16
	ds_read_b128 v[8:11], v37 offset:32
	ds_read_b128 v[12:15], v37 offset:48
	s_cbranch_scc0 .LBB0_622
	s_ashr_i32 s43, s42, 31
	v_lshl_add_u64 v[30:31], s[42:43], 2, v[32:33]
	v_lshlrev_b32_e32 v194, 2, v20
	v_lshl_add_u64 v[30:31], v[30:31], 0, v[194:195]
	s_waitcnt lgkmcnt(3)
	global_store_dwordx4 v[30:31], v[0:3], off
	s_waitcnt lgkmcnt(2)
	global_store_dwordx4 v[30:31], v[4:7], off offset:16
	s_waitcnt lgkmcnt(1)
	global_store_dwordx4 v[30:31], v[8:11], off offset:32
	s_cbranch_execnz .LBB0_617
	s_branch .LBB0_623
